# prep phase: GLA units rebalanced 6/14 between conv and non-conv workgroups; live conv loop no longer waits for the previous store
# baseline (speedup 1.0000x reference)
.LBB0_455:
	s_and_b64 vcc, exec, s[8:9]
	s_cbranch_vccz .LBB0_477
	s_mov_b64 s[6:7], -1
	s_andn2_b64 vcc, exec, s[24:25]
	v_lshrrev_b32_e32 v79, 7, v192
	v_lshrrev_b32_e32 v78, 2, v192
	s_cbranch_vccnz .LBB0_464
	v_lshlrev_b32_e32 v4, 2, v192
	v_and_b32_e32 v0, 0x7f, v192
	v_and_b32_e32 v2, 12, v4
	s_mul_i32 s3, s2, 14
	v_mov_b32_e32 v3, 0
	s_movk_i32 s6, 0x100
	v_lshlrev_b32_e32 v5, 6, v78
	v_lshlrev_b32_e32 v6, 2, v2
	v_add_u32_e32 v82, 0, v4
	s_movk_i32 s8, 0x80
	s_movk_i32 s10, 0xff
	s_movk_i32 s12, 0x17f
	s_movk_i32 s14, 0x1ff
	s_mul_i32 s16, s2, 0x700
	v_lshlrev_b32_e32 v4, 1, v0
	v_lshlrev_b32_e32 v1, 4, v79
	v_cmp_gt_u32_e64 s[6:7], s6, v192
	s_mov_b32 s25, 0
	v_add3_u32 v80, 0, v5, v6
	v_lshl_add_u32 v81, v79, 10, 0
	v_lshl_add_u32 v83, v0, 2, 0
	v_cmp_gt_u32_e64 s[8:9], s8, v192
	v_cmp_lt_u32_e64 s[10:11], s10, v192
	v_cmp_lt_u32_e64 s[12:13], s12, v192
	v_cmp_lt_u32_e64 s[14:15], s14, v192
	s_addk_i32 s3, 0xf580
	s_add_i32 s34, s16, 0xfffac000
	s_movk_i32 s35, 0x1000
	s_movk_i32 s36, 0x2000
	s_movk_i32 s37, 0x3000
	s_movk_i32 s38, 0x4000
	s_movk_i32 s39, 0x5000
	s_movk_i32 s40, 0x6000
	s_movk_i32 s41, 0x7000
	s_movk_i32 s42, 0x2c00
	v_mov_b32_e32 v6, v4
	v_mov_b32_e32 v7, v3
	v_lshlrev_b32_e32 v8, 2, v2
	s_mov_b32 s43, 0xbfb8aa3b
	s_mov_b32 s44, 0x800000
	s_mov_b32 s45, 0x3f317217
	s_mov_b32 s46, 0x7f800000
	s_mov_b32 s47, 0x3d800000
	v_lshlrev_b32_e32 v10, 2, v192
	v_mov_b32_e32 v84, 0x41b17218
	s_mov_b32 s48, 0
	s_branch .LBB0_459
.LBB0_458:
	s_or_b64 exec, exec, s[16:17]
	s_add_i32 s48, s48, 1
	s_addk_i32 s34, 0x80
	s_cmp_eq_u32 s48, 14
	s_barrier
	s_cbranch_scc1 .LBB0_463

.LBB0_469:
	s_or_b64 exec, exec, s[6:7]
	s_addk_i32 s10, 0x1000
	s_lshl_b32 s3, s3, 12
	v_or_b32_e32 v40, s10, v40
	v_or_b32_e32 v41, s3, v47
	s_movk_i32 s10, 0x2c00
	v_mov_b64_e32 v[42:43], s[8:9]
	v_mad_i64_i32 v[42:43], s[6:7], v41, s10, v[42:43]
	v_mov_b32_e32 v41, 0
	v_lshlrev_b64 v[44:45], 1, v[40:41]
	v_lshl_add_u64 v[40:41], v[42:43], 0, v[44:45]
	global_load_dwordx4 v[40:43], v[40:41], off
	v_lshl_add_u64 v[44:45], s[8:9], 0, v[44:45]
	s_mov_b32 s8, 0
	v_add_u32_e32 v46, 0, v46
	v_add_u32_e32 v48, 64, v47
	s_movk_i32 s9, 0x90
	v_mov_b32_e32 v49, 0xbd
	v_mov_b32_e32 v50, 0xbe
	v_mov_b32_e32 v51, 0xbf
	s_mov_b32 s11, 0
	s_waitcnt vmcnt(0)
.LBB0_470:
	s_nop 0
	v_lshl_add_u32 v54, s11, 6, v47
	v_mad_u64_u32 v[52:53], s[6:7], v54, s9, v[46:47]
	v_cmp_gt_i32_e64 s[6:7], 3, v54
	s_add_i32 s12, s3, s8
	v_add_u32_e32 v57, 0xc0, v54
	v_cndmask_b32_e64 v53, -3, v49, s[6:7]
	v_cmp_gt_i32_e64 s[6:7], 2, v54
	s_waitcnt vmcnt(1)
	ds_write_b128 v52, v[40:43] offset:16384
	v_add_u32_e32 v40, s12, v48
	v_cndmask_b32_e64 v55, -2, v50, s[6:7]
	v_cmp_gt_i32_e64 s[6:7], 1, v54
	v_add_u32_e32 v42, v53, v54
	v_add_u32_e32 v43, v55, v54
	v_cndmask_b32_e64 v56, -1, v51, s[6:7]
	v_cmp_gt_i32_e64 s[6:7], 0, v54
	v_add_u32_e32 v55, v56, v54
	v_add_u32_e32 v58, s12, v47
	v_cndmask_b32_e64 v54, v54, v57, s[6:7]
	v_mad_i64_i32 v[40:41], s[6:7], v40, s10, v[44:45]
	v_mad_u64_u32 v[52:53], s[6:7], v42, s9, v[46:47]
	v_mad_u64_u32 v[56:57], s[6:7], v43, s9, v[46:47]
	global_load_dwordx4 v[40:43], v[40:41], off
	v_mad_u64_u32 v[60:61], s[6:7], v55, s9, v[46:47]
	v_mad_u64_u32 v[64:65], s[6:7], v54, s9, v[46:47]
	v_mad_i64_i32 v[68:69], s[6:7], v58, s10, v[44:45]
	s_waitcnt lgkmcnt(0)
	s_barrier
	ds_read_b128 v[52:55], v52 offset:16384
	ds_read_b128 v[56:59], v56 offset:16384
	ds_read_b128 v[60:63], v60 offset:16384
	ds_read_b128 v[64:67], v64 offset:16384
	s_add_i32 s13, s11, 1
	s_waitcnt lgkmcnt(3)
	v_lshlrev_b32_e32 v70, 16, v52
	v_and_b32_e32 v71, 0xffff0000, v52
	v_lshlrev_b32_e32 v52, 16, v53
	v_and_b32_e32 v53, 0xffff0000, v53
	v_lshlrev_b32_e32 v80, 16, v54
	v_and_b32_e32 v81, 0xffff0000, v54
	v_lshlrev_b32_e32 v54, 16, v55
	v_and_b32_e32 v55, 0xffff0000, v55
	s_waitcnt lgkmcnt(2)
	v_lshlrev_b32_e32 v72, 16, v56
	v_and_b32_e32 v73, 0xffff0000, v56
	v_lshlrev_b32_e32 v56, 16, v57
	v_and_b32_e32 v57, 0xffff0000, v57
	v_lshlrev_b32_e32 v82, 16, v58
	v_and_b32_e32 v83, 0xffff0000, v58
	v_lshlrev_b32_e32 v58, 16, v59
	v_and_b32_e32 v59, 0xffff0000, v59
	v_pk_fma_f32 v[70:71], v[20:21], v[70:71], v[36:37]
	v_pk_fma_f32 v[52:53], v[22:23], v[52:53], v[38:39]
	v_pk_fma_f32 v[80:81], v[0:1], v[80:81], v[16:17]
	v_pk_fma_f32 v[54:55], v[2:3], v[54:55], v[18:19]
	s_waitcnt lgkmcnt(1)
	v_lshlrev_b32_e32 v74, 16, v60
	v_and_b32_e32 v75, 0xffff0000, v60
	v_lshlrev_b32_e32 v60, 16, v61
	v_and_b32_e32 v61, 0xffff0000, v61
	v_lshlrev_b32_e32 v84, 16, v62
	v_and_b32_e32 v85, 0xffff0000, v62
	v_lshlrev_b32_e32 v62, 16, v63
	v_and_b32_e32 v63, 0xffff0000, v63
	v_pk_fma_f32 v[70:71], v[28:29], v[72:73], v[70:71]
	v_pk_fma_f32 v[52:53], v[30:31], v[56:57], v[52:53]
	v_pk_fma_f32 v[56:57], v[8:9], v[82:83], v[80:81]
	v_pk_fma_f32 v[54:55], v[10:11], v[58:59], v[54:55]
	s_waitcnt lgkmcnt(0)
	v_lshlrev_b32_e32 v76, 16, v64
	v_and_b32_e32 v77, 0xffff0000, v64
	v_lshlrev_b32_e32 v64, 16, v65
	v_and_b32_e32 v65, 0xffff0000, v65
	v_lshlrev_b32_e32 v86, 16, v66
	v_and_b32_e32 v87, 0xffff0000, v66
	v_lshlrev_b32_e32 v66, 16, v67
	v_and_b32_e32 v67, 0xffff0000, v67
	v_pk_fma_f32 v[58:59], v[24:25], v[74:75], v[70:71]
	v_pk_fma_f32 v[52:53], v[26:27], v[60:61], v[52:53]
	v_pk_fma_f32 v[56:57], v[4:5], v[84:85], v[56:57]
	v_pk_fma_f32 v[54:55], v[6:7], v[62:63], v[54:55]
	v_pk_fma_f32 v[58:59], v[32:33], v[76:77], v[58:59]
	v_pk_fma_f32 v[52:53], v[34:35], v[64:65], v[52:53]
	v_pk_fma_f32 v[56:57], v[12:13], v[86:87], v[56:57]
	v_pk_fma_f32 v[54:55], v[14:15], v[66:67], v[54:55]
	v_mul_f32_e32 v60, 0xbfb8aa3b, v58
	v_mul_f32_e32 v61, 0xbfb8aa3b, v59
	v_mul_f32_e32 v62, 0xbfb8aa3b, v52
	v_mul_f32_e32 v63, 0xbfb8aa3b, v53
	v_mul_f32_e32 v64, 0xbfb8aa3b, v56
	v_mul_f32_e32 v65, 0xbfb8aa3b, v57
	v_mul_f32_e32 v66, 0xbfb8aa3b, v54
	v_mul_f32_e32 v67, 0xbfb8aa3b, v55
	v_exp_f32_e32 v60, v60
	v_exp_f32_e32 v61, v61
	v_exp_f32_e32 v62, v62
	v_exp_f32_e32 v63, v63
	v_exp_f32_e32 v64, v64
	v_exp_f32_e32 v65, v65
	v_exp_f32_e32 v66, v66
	v_exp_f32_e32 v67, v67
	v_add_f32_e32 v60, 1.0, v60
	v_add_f32_e32 v61, 1.0, v61
	v_add_f32_e32 v62, 1.0, v62
	v_add_f32_e32 v63, 1.0, v63
	v_add_f32_e32 v64, 1.0, v64
	v_add_f32_e32 v65, 1.0, v65
	v_add_f32_e32 v66, 1.0, v66
	v_add_f32_e32 v67, 1.0, v67
	v_rcp_f32_e32 v60, v60
	v_rcp_f32_e32 v61, v61
	v_rcp_f32_e32 v62, v62
	v_rcp_f32_e32 v63, v63
	v_rcp_f32_e32 v64, v64
	v_rcp_f32_e32 v65, v65
	v_rcp_f32_e32 v66, v66
	v_rcp_f32_e32 v67, v67
	s_cmp_lg_u32 s11, 2
	s_cselect_b32 s11, s13, 0
	s_add_i32 s8, s8, 64
	v_pk_mul_f32 v[58:59], v[58:59], v[60:61]
	v_pk_mul_f32 v[60:61], v[52:53], v[62:63]
	v_pk_mul_f32 v[56:57], v[56:57], v[64:65]
	v_pk_mul_f32 v[62:63], v[54:55], v[66:67]
	s_cmpk_lg_i32 s8, 0xfc0
	v_cvt_pk_bf16_f32 v52, v58, v59
	v_cvt_pk_bf16_f32 v53, v60, v61
	v_cvt_pk_bf16_f32 v54, v56, v57
	v_cvt_pk_bf16_f32 v55, v62, v63
	global_store_dwordx4 v[68:69], v[52:55], off
	s_cbranch_scc1 .LBB0_470
	s_or_b32 s6, s3, 0xfc0
	s_movk_i32 s3, 0x90
	v_mad_u32_u24 v56, v47, s3, v46
	s_waitcnt vmcnt(1)
	ds_write_b128 v56, v[40:43] offset:16384
	v_mov_b32_e32 v40, 0xbd
	v_cndmask_b32_e32 v40, -3, v40, vcc
	v_add_u32_e32 v40, v40, v47
	v_mad_i32_i24 v40, v40, s3, v46
	v_mov_b32_e32 v48, 0xbe
	v_cmp_gt_u32_e32 vcc, 16, v192
	s_waitcnt lgkmcnt(0)
	s_barrier
	ds_read_b128 v[40:43], v40 offset:16384
	v_cndmask_b32_e32 v48, -2, v48, vcc
	v_mov_b32_e32 v49, 0xbf
	v_cmp_gt_u32_e32 vcc, 8, v192
	v_add_u32_e32 v48, v48, v47
	v_mad_i32_i24 v48, v48, s3, v46
	v_cndmask_b32_e32 v49, -1, v49, vcc
	v_add_u32_e32 v49, v49, v47
	v_mad_i32_i24 v46, v49, s3, v46
	ds_read_b128 v[48:51], v48 offset:16384
	ds_read_b128 v[52:55], v46 offset:16384
	ds_read_b128 v[56:59], v56 offset:16384
	s_waitcnt lgkmcnt(3)
	v_lshlrev_b32_e32 v60, 16, v40
	v_and_b32_e32 v61, 0xffff0000, v40
	v_pk_fma_f32 v[20:21], v[20:21], v[60:61], v[36:37]
	s_waitcnt lgkmcnt(2)
	v_lshlrev_b32_e32 v36, 16, v48
	v_and_b32_e32 v37, 0xffff0000, v48
	v_pk_fma_f32 v[20:21], v[28:29], v[36:37], v[20:21]
	s_waitcnt lgkmcnt(1)
	v_lshlrev_b32_e32 v28, 16, v52
	v_and_b32_e32 v29, 0xffff0000, v52
	v_pk_fma_f32 v[20:21], v[24:25], v[28:29], v[20:21]
	v_lshlrev_b32_e32 v28, 16, v41
	v_and_b32_e32 v29, 0xffff0000, v41
	v_pk_fma_f32 v[22:23], v[22:23], v[28:29], v[38:39]
	v_lshlrev_b32_e32 v28, 16, v49
	v_and_b32_e32 v29, 0xffff0000, v49
	v_pk_fma_f32 v[22:23], v[30:31], v[28:29], v[22:23]
	v_lshlrev_b32_e32 v28, 16, v53
	v_and_b32_e32 v29, 0xffff0000, v53
	v_pk_fma_f32 v[22:23], v[26:27], v[28:29], v[22:23]
	v_lshlrev_b32_e32 v28, 16, v42
	v_and_b32_e32 v29, 0xffff0000, v42
	v_pk_fma_f32 v[0:1], v[0:1], v[28:29], v[16:17]
	v_lshlrev_b32_e32 v16, 16, v50
	v_and_b32_e32 v17, 0xffff0000, v50
	v_pk_fma_f32 v[0:1], v[8:9], v[16:17], v[0:1]
	v_lshlrev_b32_e32 v8, 16, v54
	v_and_b32_e32 v9, 0xffff0000, v54
	v_pk_fma_f32 v[0:1], v[4:5], v[8:9], v[0:1]
	v_lshlrev_b32_e32 v8, 16, v43
	v_and_b32_e32 v9, 0xffff0000, v43
	v_pk_fma_f32 v[2:3], v[2:3], v[8:9], v[18:19]
	v_lshlrev_b32_e32 v8, 16, v51
	v_and_b32_e32 v9, 0xffff0000, v51
	s_waitcnt lgkmcnt(0)
	v_lshlrev_b32_e32 v4, 16, v58
	v_and_b32_e32 v5, 0xffff0000, v58
	v_pk_fma_f32 v[2:3], v[10:11], v[8:9], v[2:3]
	v_lshlrev_b32_e32 v8, 16, v55
	v_and_b32_e32 v9, 0xffff0000, v55
	v_lshlrev_b32_e32 v24, 16, v56
	v_and_b32_e32 v25, 0xffff0000, v56
	v_lshlrev_b32_e32 v26, 16, v57
	v_and_b32_e32 v27, 0xffff0000, v57
	v_pk_fma_f32 v[0:1], v[12:13], v[4:5], v[0:1]
	v_pk_fma_f32 v[2:3], v[6:7], v[8:9], v[2:3]
	v_lshlrev_b32_e32 v6, 16, v59
	v_and_b32_e32 v7, 0xffff0000, v59
	v_pk_fma_f32 v[20:21], v[32:33], v[24:25], v[20:21]
	v_pk_fma_f32 v[22:23], v[34:35], v[26:27], v[22:23]
	v_mul_f32_e32 v4, 0xbfb8aa3b, v0
	v_mul_f32_e32 v5, 0xbfb8aa3b, v1
	v_pk_fma_f32 v[2:3], v[14:15], v[6:7], v[2:3]
	v_mul_f32_e32 v24, 0xbfb8aa3b, v20
	v_mul_f32_e32 v25, 0xbfb8aa3b, v21
	v_mul_f32_e32 v26, 0xbfb8aa3b, v22
	v_mul_f32_e32 v27, 0xbfb8aa3b, v23
	v_exp_f32_e32 v4, v4
	v_exp_f32_e32 v5, v5
	v_mul_f32_e32 v6, 0xbfb8aa3b, v2
	v_mul_f32_e32 v7, 0xbfb8aa3b, v3
	v_exp_f32_e32 v24, v24
	v_exp_f32_e32 v25, v25
	v_exp_f32_e32 v26, v26
	v_exp_f32_e32 v27, v27
	v_exp_f32_e32 v6, v6
	v_exp_f32_e32 v7, v7
	v_add_f32_e32 v4, 1.0, v4
	v_add_f32_e32 v5, 1.0, v5
	v_add_f32_e32 v24, 1.0, v24
	v_add_f32_e32 v25, 1.0, v25
	v_add_f32_e32 v26, 1.0, v26
	v_add_f32_e32 v27, 1.0, v27
	v_rcp_f32_e32 v4, v4
	v_rcp_f32_e32 v5, v5
	v_add_f32_e32 v6, 1.0, v6
	v_add_f32_e32 v7, 1.0, v7
	v_rcp_f32_e32 v24, v24
	v_rcp_f32_e32 v25, v25
	v_rcp_f32_e32 v26, v26
	v_rcp_f32_e32 v27, v27
	v_rcp_f32_e32 v6, v6
	v_rcp_f32_e32 v7, v7
	v_pk_mul_f32 v[4:5], v[0:1], v[4:5]
	v_pk_mul_f32 v[8:9], v[20:21], v[24:25]
	v_pk_mul_f32 v[10:11], v[22:23], v[26:27]
	v_pk_mul_f32 v[6:7], v[2:3], v[6:7]
	v_cvt_pk_bf16_f32 v2, v4, v5
	v_add_u32_e32 v4, s6, v47
	s_movk_i32 s34, 0x2c00
	v_cvt_pk_bf16_f32 v0, v8, v9
	v_cvt_pk_bf16_f32 v1, v10, v11
	v_cvt_pk_bf16_f32 v3, v6, v7
	v_mad_i64_i32 v[4:5], s[6:7], v4, s34, v[44:45]
	global_store_dwordx4 v[4:5], v[0:3], off
	v_lshlrev_b32_e32 v4, 2, v192
	s_mul_i32 s35, s2, 6
	v_and_b32_e32 v2, 12, v4
	v_and_b32_e32 v0, 0x7f, v192
	s_movk_i32 s6, 0x100
	v_lshlrev_b32_e32 v5, 6, v78
	v_lshlrev_b32_e32 v6, 2, v2
	s_movk_i32 s8, 0x80
	s_movk_i32 s10, 0xff
	s_movk_i32 s12, 0x17f
	s_movk_i32 s14, 0x1ff
	s_mul_i32 s16, s2, 0x300
	s_mov_b32 s3, 0xbfb8aa3b
	v_lshlrev_b32_e32 v1, 4, v79
	v_mov_b32_e32 v3, 0
	v_cmp_gt_u32_e64 s[6:7], s6, v192
	s_mov_b32 s25, 0
	v_add3_u32 v74, 0, v5, v6
	v_lshl_add_u32 v75, v79, 10, 0
	v_add_u32_e32 v76, 0, v4
	v_lshl_add_u32 v77, v0, 2, 0
	v_cmp_gt_u32_e64 s[8:9], s8, v192
	v_cmp_lt_u32_e64 s[10:11], s10, v192
	v_cmp_lt_u32_e64 s[12:13], s12, v192
	v_cmp_lt_u32_e64 s[14:15], s14, v192
	s_addk_i32 s35, 0x380
	s_add_i32 s36, s16, 0x1c000
	s_movk_i32 s37, 0x1000
	s_movk_i32 s38, 0x2000
	s_movk_i32 s39, 0x3000
	s_movk_i32 s40, 0x4000
	s_movk_i32 s41, 0x5000
	s_movk_i32 s42, 0x6000
	s_movk_i32 s43, 0x7000
	v_lshlrev_b32_e32 v4, 2, v2
	s_mov_b32 s44, 0x800000
	s_mov_b32 s45, 0x3f317217
	s_mov_b32 s46, 0x7f800000
	s_mov_b32 s47, 0x3d800000
	v_lshlrev_b32_e32 v2, 1, v0
	v_lshlrev_b32_e32 v6, 2, v192
	v_mov_b32_e32 v79, 0x41b17218
	s_mov_b32 s48, 0
	s_barrier
	s_branch .LBB0_473
.LBB0_472:
	s_or_b64 exec, exec, s[16:17]
	s_add_i32 s48, s48, 1
	s_addk_i32 s36, 0x80
	s_cmp_eq_u32 s48, 6
	s_barrier
	s_cbranch_scc1 .LBB0_477
